# hgrn_dstate_item staging: the 8 tile chunks (f-logit rows, V^T rows) were loaded one at a time with vmcnt(0) + ds_write before the next address; all 8 global loads are now in flight together, LDS writ
# speedup vs baseline: 1.0383x; 1.0030x over previous
.LBB0_145:
	s_ashr_i32 s0, s16, 10
	s_ashr_i32 s1, s0, 31
	s_lshl_b64 s[0:1], s[0:1], 14
	s_and_b32 s5, s20, 0x3fc0
	s_or_b32 s0, s0, s5
	s_ashr_i32 s6, s16, 1
	s_mulk_i32 s1, 0x1400
	s_mul_hi_u32 s7, s0, 0x1400
	v_mov_b32_e32 v39, v128
	s_and_b32 s4, s6, 0xffffff80
	s_and_b32 s6, s6, 0x180
	s_add_i32 s7, s7, s1
	s_mulk_i32 s0, 0x1400
	s_add_u32 s0, s88, s0
	v_and_b32_e32 v3, 0x7f, v39
	v_or_b32_e32 v0, s6, v3
	s_addc_u32 s1, s89, s7
	s_lshl_b32 s6, s6, 1
	s_add_u32 s0, s0, s6
	v_lshlrev_b32_e32 v0, 2, v0
	s_addc_u32 s1, s1, 0
	global_load_dword v2, v0, s[12:13]
	s_add_u32 s0, s0, 0x4500400
	v_mov_b32_e32 v0, v128
	s_barrier
	s_addc_u32 s1, s1, 0
	v_mov_b64_e32 v[8:9], s[0:1]
	v_ashrrev_i32_e32 v6, 4, v0
	v_lshlrev_b32_e32 v0, 4, v0
	v_mad_i64_i32 v[4:5], s[0:1], v6, s23, v[8:9]
	v_and_b32_e32 v0, 0xf0, v0
	v_lshl_add_u64 v[4:5], v[4:5], 0, v[0:1]
	v_lshl_or_b32 v0, v6, 8, v0
	global_load_dwordx4 v[148:151], v[4:5], off
	v_mov_b32_e32 v106, v0
	v_ashrrev_i32_e32 v37, 7, v39
	v_lshlrev_b32_e32 v41, 2, v3
	v_lshlrev_b32_e32 v40, 6, v37
	v_lshlrev_b32_e32 v36, 2, v39
	v_cmp_lt_u32_e32 vcc, s22, v39
	v_mov_b32_e32 v0, v128
	s_nop 0
	v_add_u32_e32 v4, 0x100, v0
	v_ashrrev_i32_e32 v6, 4, v4
	v_lshlrev_b32_e32 v0, 4, v0
	v_mad_i64_i32 v[4:5], s[0:1], v6, s23, v[8:9]
	v_and_b32_e32 v0, 0xf0, v0
	v_lshl_add_u64 v[4:5], v[4:5], 0, v[0:1]
	v_lshl_or_b32 v0, v6, 8, v0
	global_load_dwordx4 v[152:155], v[4:5], off
	v_mov_b32_e32 v107, v0
	v_mov_b32_e32 v0, v128
	s_nop 0
	v_add_u32_e32 v4, 0x200, v0
	v_ashrrev_i32_e32 v6, 4, v4
	v_lshlrev_b32_e32 v0, 4, v0
	v_mad_i64_i32 v[4:5], s[0:1], v6, s23, v[8:9]
	v_and_b32_e32 v0, 0xf0, v0
	v_lshl_add_u64 v[4:5], v[4:5], 0, v[0:1]
	v_lshl_or_b32 v0, v6, 8, v0
	global_load_dwordx4 v[156:159], v[4:5], off
	v_mov_b32_e32 v108, v0
	v_mov_b32_e32 v0, v128
	s_nop 0
	v_add_u32_e32 v4, 0x300, v0
	v_ashrrev_i32_e32 v6, 4, v4
	v_lshlrev_b32_e32 v0, 4, v0
	v_mad_i64_i32 v[4:5], s[0:1], v6, s23, v[8:9]
	v_and_b32_e32 v0, 0xf0, v0
	v_lshl_add_u64 v[4:5], v[4:5], 0, v[0:1]
	v_lshl_or_b32 v0, v6, 8, v0
	global_load_dwordx4 v[160:163], v[4:5], off
	v_mov_b32_e32 v109, v0
	s_lshl_b32 s0, s5, 1
	s_add_u32 s0, s86, s0
	s_addc_u32 s1, s87, 0
	v_mov_b32_e32 v0, v128
	s_nop 0
	v_ashrrev_i32_e32 v6, 3, v0
	v_add_u32_e32 v4, s4, v6
	v_ashrrev_i32_e32 v5, 31, v4
	v_lshlrev_b64 v[4:5], 15, v[4:5]
	v_lshlrev_b32_e32 v0, 4, v0
	v_lshl_add_u64 v[4:5], s[0:1], 0, v[4:5]
	v_and_b32_e32 v0, 0x70, v0
	v_lshl_add_u64 v[4:5], v[4:5], 0, v[0:1]
	v_mad_u64_u32 v[8:9], s[6:7], v6, s24, v[0:1]
	global_load_dwordx4 v[164:167], v[4:5], off
	v_mov_b32_e32 v110, v8
	v_mov_b32_e32 v0, v128
	s_nop 0
	v_add_u32_e32 v4, 0x100, v0
	v_ashrrev_i32_e32 v6, 3, v4
	v_add_u32_e32 v4, s4, v6
	v_ashrrev_i32_e32 v5, 31, v4
	v_lshlrev_b64 v[4:5], 15, v[4:5]
	v_lshlrev_b32_e32 v0, 4, v0
	v_lshl_add_u64 v[4:5], s[0:1], 0, v[4:5]
	v_and_b32_e32 v0, 0x70, v0
	v_lshl_add_u64 v[4:5], v[4:5], 0, v[0:1]
	v_mad_u64_u32 v[8:9], s[6:7], v6, s24, v[0:1]
	global_load_dwordx4 v[168:171], v[4:5], off
	v_mov_b32_e32 v111, v8
	v_mov_b32_e32 v0, v128
	s_nop 0
	v_add_u32_e32 v4, 0x200, v0
	v_ashrrev_i32_e32 v6, 3, v4
	v_add_u32_e32 v4, s4, v6
	v_ashrrev_i32_e32 v5, 31, v4
	v_lshlrev_b64 v[4:5], 15, v[4:5]
	v_lshlrev_b32_e32 v0, 4, v0
	v_lshl_add_u64 v[4:5], s[0:1], 0, v[4:5]
	v_and_b32_e32 v0, 0x70, v0
	v_lshl_add_u64 v[4:5], v[4:5], 0, v[0:1]
	v_mad_u64_u32 v[8:9], s[6:7], v6, s24, v[0:1]
	global_load_dwordx4 v[172:175], v[4:5], off
	v_mov_b32_e32 v112, v8
	v_mov_b32_e32 v0, v128
	s_nop 0
	v_add_u32_e32 v4, 0x300, v0
	v_ashrrev_i32_e32 v6, 3, v4
	v_add_u32_e32 v4, s4, v6
	v_ashrrev_i32_e32 v5, 31, v4
	v_lshlrev_b64 v[4:5], 15, v[4:5]
	v_lshlrev_b32_e32 v0, 4, v0
	v_lshl_add_u64 v[4:5], s[0:1], 0, v[4:5]
	v_and_b32_e32 v0, 0x70, v0
	v_lshl_add_u64 v[4:5], v[4:5], 0, v[0:1]
	v_mad_u64_u32 v[8:9], s[0:1], v6, s24, v[0:1]
	global_load_dwordx4 v[176:179], v[4:5], off
	v_mov_b32_e32 v113, v8
	s_waitcnt vmcnt(7)
	ds_write_b128 v106, v[148:151] offset:40960
	s_waitcnt vmcnt(6)
	ds_write_b128 v107, v[152:155] offset:40960
	s_waitcnt vmcnt(5)
	ds_write_b128 v108, v[156:159] offset:40960
	s_waitcnt vmcnt(4)
	ds_write_b128 v109, v[160:163] offset:40960
	s_waitcnt vmcnt(3)
	ds_write_b128 v110, v[164:167]
	s_waitcnt vmcnt(2)
	ds_write_b128 v111, v[168:171]
	s_waitcnt vmcnt(1)
	ds_write_b128 v112, v[172:175]
	s_waitcnt vmcnt(0)
	ds_write_b128 v113, v[176:179]
	v_sub_f32_e32 v0, 1.0, v2
	v_lshlrev_b32_e32 v4, 1, v3
	v_lshl_or_b32 v11, v37, 13, v4
	s_waitcnt lgkmcnt(0)
	s_barrier
	ds_read_u16 v4, v11 offset:40960
	ds_read_u16 v5, v11 offset:41216
	ds_read_u16 v6, v11 offset:41472
	ds_read_u16 v7, v11 offset:41728
	ds_read_u16 v8, v11 offset:41984
	ds_read_u16 v9, v11 offset:48384
	s_waitcnt lgkmcnt(5)
	v_lshlrev_b32_e32 v4, 16, v4
	s_waitcnt lgkmcnt(4)
	v_lshlrev_b32_e32 v5, 16, v5
	v_mul_f32_e32 v4, 0xbfb8aa3b, v4
	v_mul_f32_e32 v5, 0xbfb8aa3b, v5
	v_exp_f32_e32 v4, v4
	v_exp_f32_e32 v5, v5
	s_waitcnt lgkmcnt(3)
	v_lshlrev_b32_e32 v6, 16, v6
	s_waitcnt lgkmcnt(2)
	v_lshlrev_b32_e32 v7, 16, v7
	v_mul_f32_e32 v6, 0xbfb8aa3b, v6
	v_mul_f32_e32 v7, 0xbfb8aa3b, v7
	v_exp_f32_e32 v6, v6
	v_exp_f32_e32 v7, v7
	v_add_f32_e32 v4, 1.0, v4
	v_add_f32_e32 v5, 1.0, v5
	v_rcp_f32_e32 v4, v4
	v_rcp_f32_e32 v5, v5
	v_add_f32_e32 v6, 1.0, v6
	v_add_f32_e32 v7, 1.0, v7
	v_rcp_f32_e32 v6, v6
	v_rcp_f32_e32 v7, v7
	v_mul_u32_u24_e32 v3, 0x9c, v3
	v_pk_fma_f32 v[4:5], v[0:1], v[4:5], v[2:3] op_sel_hi:[0,1,0]
	v_cmp_gt_f32_e64 s[0:1], s25, v4
	v_add3_u32 v42, v41, v3, v40
	v_pk_fma_f32 v[6:7], v[0:1], v[6:7], v[2:3] op_sel_hi:[0,1,0]
	v_cndmask_b32_e64 v3, 0, 32, s[0:1]
	v_ldexp_f32 v3, v4, v3
	v_log_f32_e32 v3, v3
	s_waitcnt lgkmcnt(1)
	v_lshlrev_b32_e32 v8, 16, v8
	v_mul_f32_e32 v8, 0xbfb8aa3b, v8
	v_exp_f32_e32 v8, v8
	v_mul_f32_e32 v37, 0x3f317217, v3
	v_fma_f32 v37, v3, s26, -v37
	v_fmac_f32_e32 v37, 0x3377d1cf, v3
	v_fmac_f32_e32 v37, 0x3f317217, v3
	v_cmp_lt_f32_e64 s[6:7], |v3|, s27
	v_add_f32_e32 v8, 1.0, v8
	v_rcp_f32_e32 v12, v8
	v_cndmask_b32_e64 v3, v3, v37, s[6:7]
	v_cndmask_b32_e64 v37, 0, v38, s[0:1]
	ds_read_u16 v8, v11 offset:42240
	ds_read_u16 v10, v11 offset:48640
	v_sub_f32_e32 v3, v3, v37
	v_cmp_gt_f32_e64 s[0:1], s25, v5
	v_add_f32_e32 v43, 0, v3
	s_waitcnt lgkmcnt(1)
	v_lshlrev_b32_e32 v8, 16, v8
	v_cndmask_b32_e64 v3, 0, 32, s[0:1]
	v_ldexp_f32 v3, v5, v3
	v_log_f32_e32 v3, v3
	v_mul_f32_e32 v8, 0xbfb8aa3b, v8
	v_exp_f32_e32 v8, v8
	v_lshlrev_b32_e32 v9, 16, v9
	v_mul_f32_e32 v37, 0x3f317217, v3
	v_fma_f32 v37, v3, s26, -v37
	v_fmac_f32_e32 v37, 0x3377d1cf, v3
	v_fmac_f32_e32 v37, 0x3f317217, v3
	v_cmp_lt_f32_e64 s[6:7], |v3|, s27
	v_add_f32_e32 v8, 1.0, v8
	v_rcp_f32_e32 v13, v8
	v_cndmask_b32_e64 v3, v3, v37, s[6:7]
	v_cndmask_b32_e64 v37, 0, v38, s[0:1]
	ds_read_u16 v8, v11 offset:42496
	v_sub_f32_e32 v3, v3, v37
	v_cmp_gt_f32_e64 s[0:1], s25, v6
	v_add_f32_e32 v44, v43, v3
	v_mul_f32_e32 v9, 0xbfb8aa3b, v9
	v_cndmask_b32_e64 v3, 0, 32, s[0:1]
	v_ldexp_f32 v3, v6, v3
	v_log_f32_e32 v3, v3
	s_waitcnt lgkmcnt(0)
	v_lshlrev_b32_e32 v8, 16, v8
	v_mul_f32_e32 v8, 0xbfb8aa3b, v8
	v_exp_f32_e32 v8, v8
	v_mul_f32_e32 v37, 0x3f317217, v3
	v_fma_f32 v37, v3, s26, -v37
	v_fmac_f32_e32 v37, 0x3377d1cf, v3
	v_fmac_f32_e32 v37, 0x3f317217, v3
	v_cmp_lt_f32_e64 s[6:7], |v3|, s27
	v_add_f32_e32 v8, 1.0, v8
	v_rcp_f32_e32 v14, v8
	v_cndmask_b32_e64 v3, v3, v37, s[6:7]
	v_cndmask_b32_e64 v37, 0, v38, s[0:1]
	ds_read_u16 v8, v11 offset:42752
	v_sub_f32_e32 v3, v3, v37
	v_cmp_gt_f32_e64 s[0:1], s25, v7
	v_add_f32_e32 v45, v44, v3
	v_exp_f32_e32 v9, v9
	v_cndmask_b32_e64 v3, 0, 32, s[0:1]
	v_ldexp_f32 v3, v7, v3
	v_log_f32_e32 v3, v3
	s_waitcnt lgkmcnt(0)
	v_lshlrev_b32_e32 v8, 16, v8
	v_mul_f32_e32 v8, 0xbfb8aa3b, v8
	v_exp_f32_e32 v8, v8
	v_mul_f32_e32 v37, 0x3f317217, v3
	v_fma_f32 v37, v3, s26, -v37
	v_fmac_f32_e32 v37, 0x3377d1cf, v3
	v_fmac_f32_e32 v37, 0x3f317217, v3
	v_cmp_lt_f32_e64 s[6:7], |v3|, s27
	v_add_f32_e32 v8, 1.0, v8
	v_rcp_f32_e32 v15, v8
	v_cndmask_b32_e64 v3, v3, v37, s[6:7]
	v_cndmask_b32_e64 v37, 0, v38, s[0:1]
	ds_read_u16 v8, v11 offset:43008
	v_sub_f32_e32 v3, v3, v37
	v_add_f32_e32 v3, v45, v3
	v_pk_fma_f32 v[12:13], v[0:1], v[12:13], v[2:3] op_sel_hi:[0,1,0]
	v_cmp_gt_f32_e64 s[0:1], s25, v12
	s_waitcnt lgkmcnt(0)
	v_lshlrev_b32_e32 v8, 16, v8
	v_mul_f32_e32 v8, 0xbfb8aa3b, v8
	v_cndmask_b32_e64 v37, 0, 32, s[0:1]
	v_ldexp_f32 v37, v12, v37
	v_log_f32_e32 v37, v37
	v_exp_f32_e32 v8, v8
	v_pk_fma_f32 v[14:15], v[0:1], v[14:15], v[2:3] op_sel_hi:[0,1,0]
	v_lshlrev_b32_e32 v10, 16, v10
	v_mul_f32_e32 v46, 0x3f317217, v37
	v_add_f32_e32 v8, 1.0, v8
	v_fma_f32 v46, v37, s26, -v46
	v_rcp_f32_e32 v20, v8
	ds_read_u16 v8, v11 offset:43264
	v_fmac_f32_e32 v46, 0x3377d1cf, v37
	v_fmac_f32_e32 v46, 0x3f317217, v37
	v_cmp_lt_f32_e64 s[6:7], |v37|, s27
	v_mul_f32_e32 v10, 0xbfb8aa3b, v10
	s_waitcnt lgkmcnt(0)
	v_lshlrev_b32_e32 v8, 16, v8
	v_cndmask_b32_e64 v37, v37, v46, s[6:7]
	v_cndmask_b32_e64 v46, 0, v38, s[0:1]
	v_cmp_gt_f32_e64 s[0:1], s25, v13
	v_sub_f32_e32 v37, v37, v46
	v_mul_f32_e32 v8, 0xbfb8aa3b, v8
	v_cndmask_b32_e64 v46, 0, 32, s[0:1]
	v_ldexp_f32 v46, v13, v46
	v_log_f32_e32 v46, v46
	v_exp_f32_e32 v8, v8
	v_exp_f32_e32 v10, v10
	v_add_f32_e32 v9, 1.0, v9
	v_mul_f32_e32 v47, 0x3f317217, v46
	v_fma_f32 v47, v46, s26, -v47
	v_add_f32_e32 v8, 1.0, v8
	v_fmac_f32_e32 v47, 0x3377d1cf, v46
	v_rcp_f32_e32 v21, v8
	ds_read_u16 v8, v11 offset:43520
	v_fmac_f32_e32 v47, 0x3f317217, v46
	v_cmp_lt_f32_e64 s[6:7], |v46|, s27
	v_pk_fma_f32 v[20:21], v[0:1], v[20:21], v[2:3] op_sel_hi:[0,1,0]
	v_rcp_f32_e32 v9, v9
	v_cndmask_b32_e64 v46, v46, v47, s[6:7]
	v_cndmask_b32_e64 v47, 0, v38, s[0:1]
	v_cmp_gt_f32_e64 s[0:1], s25, v14
	v_sub_f32_e32 v46, v46, v47
	s_waitcnt lgkmcnt(0)
	v_lshlrev_b32_e32 v8, 16, v8
	v_cndmask_b32_e64 v47, 0, 32, s[0:1]
	v_ldexp_f32 v47, v14, v47
	v_log_f32_e32 v47, v47
	v_mul_f32_e32 v8, 0xbfb8aa3b, v8
	v_exp_f32_e32 v8, v8
	v_add_f32_e32 v10, 1.0, v10
	v_mul_f32_e32 v48, 0x3f317217, v47
	v_fma_f32 v48, v47, s26, -v48
	v_fmac_f32_e32 v48, 0x3377d1cf, v47
	v_add_f32_e32 v8, 1.0, v8
	v_fmac_f32_e32 v48, 0x3f317217, v47
	v_cmp_lt_f32_e64 s[6:7], |v47|, s27
	v_rcp_f32_e32 v22, v8
	ds_read_u16 v8, v11 offset:43776
	v_cndmask_b32_e64 v47, v47, v48, s[6:7]
	v_cndmask_b32_e64 v48, 0, v38, s[0:1]
	v_cmp_gt_f32_e64 s[0:1], s25, v15
	v_sub_f32_e32 v47, v47, v48
	s_waitcnt lgkmcnt(0)
	v_lshlrev_b32_e32 v8, 16, v8
	v_cndmask_b32_e64 v48, 0, 32, s[0:1]
	v_ldexp_f32 v48, v15, v48
	v_log_f32_e32 v48, v48
	v_mul_f32_e32 v8, 0xbfb8aa3b, v8
	v_exp_f32_e32 v8, v8
	v_rcp_f32_e32 v10, v10
	v_mul_f32_e32 v49, 0x3f317217, v48
	v_fma_f32 v49, v48, s26, -v49
	v_fmac_f32_e32 v49, 0x3377d1cf, v48
	v_fmac_f32_e32 v49, 0x3f317217, v48
	v_cmp_lt_f32_e64 s[6:7], |v48|, s27
	v_add_f32_e32 v8, 1.0, v8
	v_rcp_f32_e32 v23, v8
	v_cndmask_b32_e64 v48, v48, v49, s[6:7]
	v_cndmask_b32_e64 v49, 0, v38, s[0:1]
	v_cmp_gt_f32_e64 s[0:1], s25, v20
	ds_read_u16 v8, v11 offset:44032
	v_sub_f32_e32 v50, v48, v49
	v_add_f32_e32 v49, v3, v37
	v_cndmask_b32_e64 v37, 0, 32, s[0:1]
	v_ldexp_f32 v37, v20, v37
	v_log_f32_e32 v37, v37
	v_add_f32_e32 v48, v49, v46
	s_waitcnt lgkmcnt(0)
	v_lshlrev_b32_e32 v8, 16, v8
	v_add_f32_e32 v47, v48, v47
	v_mul_f32_e32 v8, 0xbfb8aa3b, v8
	v_add_f32_e32 v46, v47, v50
	v_mul_f32_e32 v50, 0x3f317217, v37
	v_exp_f32_e32 v8, v8
	v_fma_f32 v50, v37, s26, -v50
	v_fmac_f32_e32 v50, 0x3377d1cf, v37
	v_fmac_f32_e32 v50, 0x3f317217, v37
	v_cmp_lt_f32_e64 s[6:7], |v37|, s27
	v_add_f32_e32 v8, 1.0, v8
	v_rcp_f32_e32 v28, v8
	v_cndmask_b32_e64 v37, v37, v50, s[6:7]
	v_cndmask_b32_e64 v50, 0, v38, s[0:1]
	v_cmp_gt_f32_e64 s[0:1], s25, v21
	v_sub_f32_e32 v37, v37, v50
	ds_read_u16 v8, v11 offset:44288
	v_cndmask_b32_e64 v50, 0, 32, s[0:1]
	v_ldexp_f32 v50, v21, v50
	v_log_f32_e32 v50, v50
	v_pk_fma_f32 v[22:23], v[0:1], v[22:23], v[2:3] op_sel_hi:[0,1,0]
	s_waitcnt lgkmcnt(0)
	v_lshlrev_b32_e32 v8, 16, v8
	v_mul_f32_e32 v8, 0xbfb8aa3b, v8
	v_mul_f32_e32 v51, 0x3f317217, v50
	v_fma_f32 v51, v50, s26, -v51
	v_exp_f32_e32 v8, v8
	v_fmac_f32_e32 v51, 0x3377d1cf, v50
	v_fmac_f32_e32 v51, 0x3f317217, v50
	v_cmp_lt_f32_e64 s[6:7], |v50|, s27
	v_add_f32_e32 v8, 1.0, v8
	v_rcp_f32_e32 v29, v8
	v_cndmask_b32_e64 v50, v50, v51, s[6:7]
	v_cndmask_b32_e64 v51, 0, v38, s[0:1]
	v_cmp_gt_f32_e64 s[0:1], s25, v22
	v_sub_f32_e32 v50, v50, v51
	ds_read_u16 v8, v11 offset:44544
	v_cndmask_b32_e64 v51, 0, 32, s[0:1]
	v_ldexp_f32 v51, v22, v51
	v_log_f32_e32 v51, v51
	v_pk_fma_f32 v[28:29], v[0:1], v[28:29], v[2:3] op_sel_hi:[0,1,0]
	s_waitcnt lgkmcnt(0)
	v_lshlrev_b32_e32 v8, 16, v8
	v_mul_f32_e32 v8, 0xbfb8aa3b, v8
	v_mul_f32_e32 v52, 0x3f317217, v51
	v_fma_f32 v52, v51, s26, -v52
	v_fmac_f32_e32 v52, 0x3377d1cf, v51
	v_exp_f32_e32 v8, v8
	v_fmac_f32_e32 v52, 0x3f317217, v51
	v_cmp_lt_f32_e64 s[6:7], |v51|, s27
	v_sub_f32_e32 v5, 1.0, v5
	v_add_f32_e32 v8, 1.0, v8
	v_cndmask_b32_e64 v51, v51, v52, s[6:7]
	v_cndmask_b32_e64 v52, 0, v38, s[0:1]
	v_cmp_gt_f32_e64 s[0:1], s25, v23
	v_sub_f32_e32 v51, v51, v52
	v_rcp_f32_e32 v30, v8
	v_cndmask_b32_e64 v52, 0, 32, s[0:1]
	v_ldexp_f32 v52, v23, v52
	v_log_f32_e32 v52, v52
	ds_read_u16 v8, v11 offset:44800
	v_sub_f32_e32 v4, 1.0, v4
	v_sub_f32_e32 v7, 1.0, v7
	v_mul_f32_e32 v53, 0x3f317217, v52
	v_fma_f32 v53, v52, s26, -v53
	s_waitcnt lgkmcnt(0)
	v_lshlrev_b32_e32 v8, 16, v8
	v_fmac_f32_e32 v53, 0x3377d1cf, v52
	v_mul_f32_e32 v8, 0xbfb8aa3b, v8
	v_fmac_f32_e32 v53, 0x3f317217, v52
	v_cmp_lt_f32_e64 s[6:7], |v52|, s27
	v_exp_f32_e32 v8, v8
	v_sub_f32_e32 v6, 1.0, v6
	v_cndmask_b32_e64 v52, v52, v53, s[6:7]
	v_cndmask_b32_e64 v53, 0, v38, s[0:1]
	v_cmp_gt_f32_e64 s[0:1], s25, v28
	v_sub_f32_e32 v54, v52, v53
	v_add_f32_e32 v53, v46, v37
	v_cndmask_b32_e64 v37, 0, 32, s[0:1]
	v_ldexp_f32 v37, v28, v37
	v_log_f32_e32 v37, v37
	v_add_f32_e32 v8, 1.0, v8
	v_rcp_f32_e32 v31, v8
	ds_read_u16 v8, v11 offset:45056
	v_add_f32_e32 v52, v53, v50
	v_add_f32_e32 v51, v52, v51
	v_add_f32_e32 v50, v51, v54
	v_mul_f32_e32 v54, 0x3f317217, v37
	v_fma_f32 v54, v37, s26, -v54
	v_fmac_f32_e32 v54, 0x3377d1cf, v37
	s_waitcnt lgkmcnt(0)
	v_lshlrev_b32_e32 v8, 16, v8
	v_fmac_f32_e32 v54, 0x3f317217, v37
	v_cmp_lt_f32_e64 s[6:7], |v37|, s27
	v_mul_f32_e32 v8, 0xbfb8aa3b, v8
	v_exp_f32_e32 v8, v8
	v_cndmask_b32_e64 v37, v37, v54, s[6:7]
	v_cndmask_b32_e64 v54, 0, v38, s[0:1]
	v_cmp_gt_f32_e64 s[0:1], s25, v29
	v_sub_f32_e32 v37, v37, v54
	v_add_f32_e32 v8, 1.0, v8
	v_cndmask_b32_e64 v54, 0, 32, s[0:1]
	v_ldexp_f32 v54, v29, v54
	v_log_f32_e32 v54, v54
	v_rcp_f32_e32 v32, v8
	ds_read_u16 v8, v11 offset:45312
	v_pk_fma_f32 v[30:31], v[0:1], v[30:31], v[2:3] op_sel_hi:[0,1,0]
	v_mul_f32_e32 v55, 0x3f317217, v54
	v_fma_f32 v55, v54, s26, -v55
	v_fmac_f32_e32 v55, 0x3377d1cf, v54
	v_fmac_f32_e32 v55, 0x3f317217, v54
	v_cmp_lt_f32_e64 s[6:7], |v54|, s27
	s_waitcnt lgkmcnt(0)
	v_lshlrev_b32_e32 v8, 16, v8
	v_mul_f32_e32 v8, 0xbfb8aa3b, v8
	v_cndmask_b32_e64 v54, v54, v55, s[6:7]
	v_cndmask_b32_e64 v55, 0, v38, s[0:1]
	v_cmp_gt_f32_e64 s[0:1], s25, v30
	v_sub_f32_e32 v54, v54, v55
	v_exp_f32_e32 v8, v8
	v_cndmask_b32_e64 v55, 0, 32, s[0:1]
	v_ldexp_f32 v55, v30, v55
	v_log_f32_e32 v55, v55
	v_add_f32_e32 v8, 1.0, v8
	v_rcp_f32_e32 v33, v8
	ds_read_u16 v8, v11 offset:45568
	v_mul_f32_e32 v56, 0x3f317217, v55
	v_fma_f32 v56, v55, s26, -v56
	v_fmac_f32_e32 v56, 0x3377d1cf, v55
	v_fmac_f32_e32 v56, 0x3f317217, v55
	v_cmp_lt_f32_e64 s[6:7], |v55|, s27
	s_waitcnt lgkmcnt(0)
	v_lshlrev_b32_e32 v8, 16, v8
	v_mul_f32_e32 v8, 0xbfb8aa3b, v8
	v_cndmask_b32_e64 v55, v55, v56, s[6:7]
	v_cndmask_b32_e64 v56, 0, v38, s[0:1]
	v_cmp_gt_f32_e64 s[0:1], s25, v31
	v_sub_f32_e32 v55, v55, v56
	v_exp_f32_e32 v8, v8
	v_cndmask_b32_e64 v56, 0, 32, s[0:1]
	v_ldexp_f32 v56, v31, v56
	v_log_f32_e32 v56, v56
	v_add_f32_e32 v8, 1.0, v8
	v_rcp_f32_e32 v34, v8
	ds_read_u16 v8, v11 offset:45824
	v_mul_f32_e32 v57, 0x3f317217, v56
	v_fma_f32 v57, v56, s26, -v57
	v_fmac_f32_e32 v57, 0x3377d1cf, v56
	v_fmac_f32_e32 v57, 0x3f317217, v56
	v_cmp_lt_f32_e64 s[6:7], |v56|, s27
	v_pk_fma_f32 v[32:33], v[0:1], v[32:33], v[2:3] op_sel_hi:[0,1,0]
	s_waitcnt lgkmcnt(0)
	v_lshlrev_b32_e32 v8, 16, v8
	v_cndmask_b32_e64 v56, v56, v57, s[6:7]
	v_cndmask_b32_e64 v57, 0, v38, s[0:1]
	v_cmp_gt_f32_e64 s[0:1], s25, v32
	v_sub_f32_e32 v58, v56, v57
	v_add_f32_e32 v57, v50, v37
	v_cndmask_b32_e64 v37, 0, 32, s[0:1]
	v_ldexp_f32 v37, v32, v37
	v_mul_f32_e32 v8, 0xbfb8aa3b, v8
	v_log_f32_e32 v37, v37
	v_exp_f32_e32 v8, v8
	v_add_f32_e32 v56, v57, v54
	v_add_f32_e32 v55, v56, v55
	v_add_f32_e32 v54, v55, v58
	v_mul_f32_e32 v58, 0x3f317217, v37
	v_add_f32_e32 v8, 1.0, v8
	v_fma_f32 v58, v37, s26, -v58
	v_rcp_f32_e32 v35, v8
	ds_read_u16 v8, v11 offset:46080
	v_fmac_f32_e32 v58, 0x3377d1cf, v37
	v_fmac_f32_e32 v58, 0x3f317217, v37
	v_cmp_lt_f32_e64 s[6:7], |v37|, s27
	v_pk_fma_f32 v[34:35], v[0:1], v[34:35], v[2:3] op_sel_hi:[0,1,0]
	s_waitcnt lgkmcnt(0)
	v_lshlrev_b32_e32 v8, 16, v8
	v_cndmask_b32_e64 v37, v37, v58, s[6:7]
	v_cndmask_b32_e64 v58, 0, v38, s[0:1]
	v_cmp_gt_f32_e64 s[0:1], s25, v33
	v_sub_f32_e32 v37, v37, v58
	v_mul_f32_e32 v8, 0xbfb8aa3b, v8
	v_cndmask_b32_e64 v58, 0, 32, s[0:1]
	v_ldexp_f32 v58, v33, v58
	v_log_f32_e32 v58, v58
	v_exp_f32_e32 v8, v8
	v_sub_f32_e32 v13, 1.0, v13
	v_sub_f32_e32 v12, 1.0, v12
	v_mul_f32_e32 v59, 0x3f317217, v58
	v_fma_f32 v59, v58, s26, -v59
	v_add_f32_e32 v8, 1.0, v8
	v_fmac_f32_e32 v59, 0x3377d1cf, v58
	v_rcp_f32_e32 v24, v8
	ds_read_u16 v8, v11 offset:46336
	v_fmac_f32_e32 v59, 0x3f317217, v58
	v_cmp_lt_f32_e64 s[6:7], |v58|, s27
	v_sub_f32_e32 v15, 1.0, v15
	v_sub_f32_e32 v14, 1.0, v14
	v_cndmask_b32_e64 v58, v58, v59, s[6:7]
	v_cndmask_b32_e64 v59, 0, v38, s[0:1]
	v_cmp_gt_f32_e64 s[0:1], s25, v34
	v_sub_f32_e32 v58, v58, v59
	s_waitcnt lgkmcnt(0)
	v_lshlrev_b32_e32 v8, 16, v8
	v_cndmask_b32_e64 v59, 0, 32, s[0:1]
	v_ldexp_f32 v59, v34, v59
	v_log_f32_e32 v59, v59
	v_mul_f32_e32 v8, 0xbfb8aa3b, v8
	v_exp_f32_e32 v8, v8
	v_sub_f32_e32 v21, 1.0, v21
	v_mul_f32_e32 v60, 0x3f317217, v59
	v_fma_f32 v60, v59, s26, -v60
	v_fmac_f32_e32 v60, 0x3377d1cf, v59
	v_add_f32_e32 v8, 1.0, v8
	v_fmac_f32_e32 v60, 0x3f317217, v59
	v_cmp_lt_f32_e64 s[6:7], |v59|, s27
	v_rcp_f32_e32 v25, v8
	ds_read_u16 v8, v11 offset:46592
	v_cndmask_b32_e64 v59, v59, v60, s[6:7]
	v_cndmask_b32_e64 v60, 0, v38, s[0:1]
	v_cmp_gt_f32_e64 s[0:1], s25, v35
	v_sub_f32_e32 v59, v59, v60
	s_waitcnt lgkmcnt(0)
	v_lshlrev_b32_e32 v8, 16, v8
	v_cndmask_b32_e64 v60, 0, 32, s[0:1]
	v_ldexp_f32 v60, v35, v60
	v_log_f32_e32 v60, v60
	v_mul_f32_e32 v8, 0xbfb8aa3b, v8
	v_exp_f32_e32 v8, v8
	v_pk_fma_f32 v[24:25], v[0:1], v[24:25], v[2:3] op_sel_hi:[0,1,0]
	v_mul_f32_e32 v61, 0x3f317217, v60
	v_fma_f32 v61, v60, s26, -v61
	v_fmac_f32_e32 v61, 0x3377d1cf, v60
	v_fmac_f32_e32 v61, 0x3f317217, v60
	v_cmp_lt_f32_e64 s[6:7], |v60|, s27
	v_add_f32_e32 v8, 1.0, v8
	v_rcp_f32_e32 v26, v8
	v_cndmask_b32_e64 v60, v60, v61, s[6:7]
	v_cndmask_b32_e64 v61, 0, v38, s[0:1]
	v_cmp_gt_f32_e64 s[0:1], s25, v24
	ds_read_u16 v8, v11 offset:46848
	v_sub_f32_e32 v62, v60, v61
	v_add_f32_e32 v61, v54, v37
	v_cndmask_b32_e64 v37, 0, 32, s[0:1]
	v_ldexp_f32 v37, v24, v37
	v_log_f32_e32 v37, v37
	v_add_f32_e32 v60, v61, v58
	s_waitcnt lgkmcnt(0)
	v_lshlrev_b32_e32 v8, 16, v8
	v_add_f32_e32 v59, v60, v59
	v_mul_f32_e32 v8, 0xbfb8aa3b, v8
	v_add_f32_e32 v58, v59, v62
	v_mul_f32_e32 v62, 0x3f317217, v37
	v_exp_f32_e32 v8, v8
	v_fma_f32 v62, v37, s26, -v62
	v_fmac_f32_e32 v62, 0x3377d1cf, v37
	v_fmac_f32_e32 v62, 0x3f317217, v37
	v_cmp_lt_f32_e64 s[6:7], |v37|, s27
	v_add_f32_e32 v8, 1.0, v8
	v_rcp_f32_e32 v27, v8
	v_cndmask_b32_e64 v37, v37, v62, s[6:7]
	v_cndmask_b32_e64 v62, 0, v38, s[0:1]
	v_cmp_gt_f32_e64 s[0:1], s25, v25
	v_sub_f32_e32 v37, v37, v62
	ds_read_u16 v8, v11 offset:47104
	v_cndmask_b32_e64 v62, 0, 32, s[0:1]
	v_ldexp_f32 v62, v25, v62
	v_log_f32_e32 v62, v62
	v_pk_fma_f32 v[26:27], v[0:1], v[26:27], v[2:3] op_sel_hi:[0,1,0]
	s_waitcnt lgkmcnt(0)
	v_lshlrev_b32_e32 v8, 16, v8
	v_mul_f32_e32 v8, 0xbfb8aa3b, v8
	v_mul_f32_e32 v63, 0x3f317217, v62
	v_fma_f32 v63, v62, s26, -v63
	v_exp_f32_e32 v8, v8
	v_fmac_f32_e32 v63, 0x3377d1cf, v62
	v_fmac_f32_e32 v63, 0x3f317217, v62
	v_cmp_lt_f32_e64 s[6:7], |v62|, s27
	v_add_f32_e32 v8, 1.0, v8
	v_rcp_f32_e32 v16, v8
	v_cndmask_b32_e64 v62, v62, v63, s[6:7]
	v_cndmask_b32_e64 v63, 0, v38, s[0:1]
	v_cmp_gt_f32_e64 s[0:1], s25, v26
	v_sub_f32_e32 v62, v62, v63
	ds_read_u16 v8, v11 offset:47360
	v_cndmask_b32_e64 v63, 0, 32, s[0:1]
	v_ldexp_f32 v63, v26, v63
	v_log_f32_e32 v63, v63
	v_sub_f32_e32 v20, 1.0, v20
	s_waitcnt lgkmcnt(0)
	v_lshlrev_b32_e32 v8, 16, v8
	v_mul_f32_e32 v8, 0xbfb8aa3b, v8
	v_mul_f32_e32 v64, 0x3f317217, v63
	v_fma_f32 v64, v63, s26, -v64
	v_fmac_f32_e32 v64, 0x3377d1cf, v63
	v_exp_f32_e32 v8, v8
	v_fmac_f32_e32 v64, 0x3f317217, v63
	v_cmp_lt_f32_e64 s[6:7], |v63|, s27
	v_sub_f32_e32 v23, 1.0, v23
	v_add_f32_e32 v8, 1.0, v8
	v_cndmask_b32_e64 v63, v63, v64, s[6:7]
	v_cndmask_b32_e64 v64, 0, v38, s[0:1]
	v_cmp_gt_f32_e64 s[0:1], s25, v27
	v_sub_f32_e32 v63, v63, v64
	v_rcp_f32_e32 v17, v8
	v_cndmask_b32_e64 v64, 0, 32, s[0:1]
	v_ldexp_f32 v64, v27, v64
	v_log_f32_e32 v64, v64
	ds_read_u16 v8, v11 offset:47616
	v_pk_fma_f32 v[16:17], v[0:1], v[16:17], v[2:3] op_sel_hi:[0,1,0]
	v_sub_f32_e32 v22, 1.0, v22
	v_mul_f32_e32 v65, 0x3f317217, v64
	v_fma_f32 v65, v64, s26, -v65
	s_waitcnt lgkmcnt(0)
	v_lshlrev_b32_e32 v8, 16, v8
	v_fmac_f32_e32 v65, 0x3377d1cf, v64
	v_mul_f32_e32 v8, 0xbfb8aa3b, v8
	v_fmac_f32_e32 v65, 0x3f317217, v64
	v_cmp_lt_f32_e64 s[6:7], |v64|, s27
	v_exp_f32_e32 v8, v8
	v_sub_f32_e32 v29, 1.0, v29
	v_cndmask_b32_e64 v64, v64, v65, s[6:7]
	v_cndmask_b32_e64 v65, 0, v38, s[0:1]
	v_cmp_gt_f32_e64 s[0:1], s25, v16
	v_sub_f32_e32 v66, v64, v65
	v_add_f32_e32 v65, v58, v37
	v_cndmask_b32_e64 v37, 0, 32, s[0:1]
	v_ldexp_f32 v37, v16, v37
	v_log_f32_e32 v37, v37
	v_add_f32_e32 v8, 1.0, v8
	v_rcp_f32_e32 v18, v8
	ds_read_u16 v8, v11 offset:47872
	v_add_f32_e32 v64, v65, v62
	v_add_f32_e32 v63, v64, v63
	v_add_f32_e32 v62, v63, v66
	v_mul_f32_e32 v66, 0x3f317217, v37
	v_fma_f32 v66, v37, s26, -v66
	v_fmac_f32_e32 v66, 0x3377d1cf, v37
	s_waitcnt lgkmcnt(0)
	v_lshlrev_b32_e32 v8, 16, v8
	v_fmac_f32_e32 v66, 0x3f317217, v37
	v_cmp_lt_f32_e64 s[6:7], |v37|, s27
	v_mul_f32_e32 v8, 0xbfb8aa3b, v8
	v_exp_f32_e32 v8, v8
	v_cndmask_b32_e64 v37, v37, v66, s[6:7]
	v_cndmask_b32_e64 v66, 0, v38, s[0:1]
	v_cmp_gt_f32_e64 s[0:1], s25, v17
	v_sub_f32_e32 v37, v37, v66
	v_add_f32_e32 v8, 1.0, v8
	v_cndmask_b32_e64 v66, 0, 32, s[0:1]
	v_ldexp_f32 v66, v17, v66
	v_log_f32_e32 v66, v66
	v_rcp_f32_e32 v19, v8
	ds_read_u16 v8, v11 offset:48128
	ds_read_u16 v11, v11 offset:48896
	v_mul_f32_e32 v67, 0x3f317217, v66
	v_fma_f32 v67, v66, s26, -v67
	v_fmac_f32_e32 v67, 0x3377d1cf, v66
	v_pk_fma_f32 v[18:19], v[0:1], v[18:19], v[2:3] op_sel_hi:[0,1,0]
	v_fmac_f32_e32 v67, 0x3f317217, v66
	v_cmp_lt_f32_e64 s[6:7], |v66|, s27
	s_waitcnt lgkmcnt(1)
	v_lshlrev_b32_e32 v8, 16, v8
	v_mul_f32_e32 v8, 0xbfb8aa3b, v8
	v_cndmask_b32_e64 v66, v66, v67, s[6:7]
	v_cndmask_b32_e64 v67, 0, v38, s[0:1]
	v_cmp_gt_f32_e64 s[0:1], s25, v18
	v_sub_f32_e32 v66, v66, v67
	v_exp_f32_e32 v8, v8
	v_cndmask_b32_e64 v67, 0, 32, s[0:1]
	v_ldexp_f32 v67, v18, v67
	v_log_f32_e32 v67, v67
	s_waitcnt lgkmcnt(0)
	v_lshlrev_b32_e32 v11, 16, v11
	v_mul_f32_e32 v11, 0xbfb8aa3b, v11
	v_exp_f32_e32 v11, v11
	v_mul_f32_e32 v68, 0x3f317217, v67
	v_fma_f32 v68, v67, s26, -v68
	v_fmac_f32_e32 v68, 0x3377d1cf, v67
	v_fmac_f32_e32 v68, 0x3f317217, v67
	v_cmp_lt_f32_e64 s[6:7], |v67|, s27
	v_add_f32_e32 v8, 1.0, v8
	v_rcp_f32_e32 v8, v8
	v_cndmask_b32_e64 v67, v67, v68, s[6:7]
	v_cndmask_b32_e64 v68, 0, v38, s[0:1]
	v_cmp_gt_f32_e64 s[0:1], s25, v19
	v_sub_f32_e32 v67, v67, v68
	v_add_f32_e32 v11, 1.0, v11
	v_cndmask_b32_e64 v68, 0, 32, s[0:1]
	v_ldexp_f32 v68, v19, v68
	v_log_f32_e32 v68, v68
	v_rcp_f32_e32 v11, v11
	v_pk_fma_f32 v[8:9], v[0:1], v[8:9], v[2:3] op_sel_hi:[0,1,0]
	v_sub_f32_e32 v28, 1.0, v28
	v_mul_f32_e32 v69, 0x3f317217, v68
	v_fma_f32 v69, v68, s26, -v69
	v_fmac_f32_e32 v69, 0x3377d1cf, v68
	v_fmac_f32_e32 v69, 0x3f317217, v68
	v_cmp_lt_f32_e64 s[6:7], |v68|, s27
	v_pk_fma_f32 v[10:11], v[0:1], v[10:11], v[2:3] op_sel_hi:[0,1,0]
	v_sub_f32_e32 v31, 1.0, v31
	v_cndmask_b32_e64 v68, v68, v69, s[6:7]
	v_cndmask_b32_e64 v69, 0, v38, s[0:1]
	v_cmp_gt_f32_e64 s[0:1], s25, v8
	v_sub_f32_e32 v70, v68, v69
	v_add_f32_e32 v69, v62, v37
	v_cndmask_b32_e64 v0, 0, 32, s[0:1]
	v_ldexp_f32 v0, v8, v0
	v_log_f32_e32 v0, v0
	v_add_f32_e32 v68, v69, v66
	v_add_f32_e32 v67, v68, v67
	v_add_f32_e32 v66, v67, v70
	v_mul_f32_e32 v2, 0x3f317217, v0
	v_fma_f32 v2, v0, s26, -v2
	v_fmac_f32_e32 v2, 0x3377d1cf, v0
	v_fmac_f32_e32 v2, 0x3f317217, v0
	v_cmp_lt_f32_e64 s[6:7], |v0|, s27
	v_sub_f32_e32 v30, 1.0, v30
	v_sub_f32_e32 v33, 1.0, v33
	v_cndmask_b32_e64 v0, v0, v2, s[6:7]
	v_cndmask_b32_e64 v2, 0, v38, s[0:1]
	v_cmp_gt_f32_e64 s[0:1], s25, v9
	v_sub_f32_e32 v0, v0, v2
	v_add_f32_e32 v0, v66, v0
	v_cndmask_b32_e64 v2, 0, 32, s[0:1]
	v_ldexp_f32 v2, v9, v2
	v_log_f32_e32 v2, v2
	v_sub_f32_e32 v32, 1.0, v32
	v_sub_f32_e32 v35, 1.0, v35
	v_sub_f32_e32 v34, 1.0, v34
	v_mul_f32_e32 v37, 0x3f317217, v2
	v_fma_f32 v37, v2, s26, -v37
	v_fmac_f32_e32 v37, 0x3377d1cf, v2
	v_fmac_f32_e32 v37, 0x3f317217, v2
	v_cmp_lt_f32_e64 s[6:7], |v2|, s27
	v_sub_f32_e32 v25, 1.0, v25
	v_sub_f32_e32 v24, 1.0, v24
	v_cndmask_b32_e64 v2, v2, v37, s[6:7]
	v_cndmask_b32_e64 v37, 0, v38, s[0:1]
	v_cmp_gt_f32_e64 s[0:1], s25, v10
	v_sub_f32_e32 v2, v2, v37
	v_add_f32_e32 v72, v0, v2
	v_cndmask_b32_e64 v37, 0, 32, s[0:1]
	v_ldexp_f32 v37, v10, v37
	v_log_f32_e32 v37, v37
	v_sub_f32_e32 v27, 1.0, v27
	v_sub_f32_e32 v26, 1.0, v26
	v_sub_f32_e32 v17, 1.0, v17
	v_mul_f32_e32 v70, 0x3f317217, v37
	v_fma_f32 v70, v37, s26, -v70
	v_fmac_f32_e32 v70, 0x3377d1cf, v37
	v_fmac_f32_e32 v70, 0x3f317217, v37
	v_cmp_lt_f32_e64 s[6:7], |v37|, s27
	v_sub_f32_e32 v16, 1.0, v16
	v_sub_f32_e32 v19, 1.0, v19
	v_cndmask_b32_e64 v37, v37, v70, s[6:7]
	v_cndmask_b32_e64 v70, 0, v38, s[0:1]
	v_cmp_gt_f32_e64 s[0:1], s25, v11
	v_sub_f32_e32 v37, v37, v70
	v_add_f32_e32 v73, v72, v37
	v_cndmask_b32_e64 v70, 0, 32, s[0:1]
	v_ldexp_f32 v70, v11, v70
	v_log_f32_e32 v70, v70
	v_sub_f32_e32 v18, 1.0, v18
	v_sub_f32_e32 v9, 1.0, v9
	v_sub_f32_e32 v8, 1.0, v8
	v_mul_f32_e32 v71, 0x3f317217, v70
	v_fma_f32 v71, v70, s26, -v71
	v_fmac_f32_e32 v71, 0x3377d1cf, v70
	v_fmac_f32_e32 v71, 0x3f317217, v70
	v_cmp_lt_f32_e64 s[6:7], |v70|, s27
	v_sub_f32_e32 v11, 1.0, v11
	v_sub_f32_e32 v10, 1.0, v10
	v_cndmask_b32_e64 v70, v70, v71, s[6:7]
	v_cndmask_b32_e64 v71, 0, v38, s[0:1]
	v_sub_f32_e32 v70, v70, v71
	v_add_f32_e32 v74, v73, v70
	ds_write_b32 v36, v74 offset:57344
	s_waitcnt lgkmcnt(0)
	s_barrier
	ds_read2st64_b32 v[70:71], v41 offset0:224 offset1:226
	s_waitcnt lgkmcnt(0)
	v_cndmask_b32_e32 v37, 0, v70, vcc
	v_mov_b32_e32 v2, v70
	v_mov_b32_e32 v36, v71
	v_add_f32_e32 v43, v43, v37
	v_pk_add_f32 v[2:3], v[2:3], v[36:37]
	v_add_f32_e32 v75, v44, v37
	v_sub_f32_e32 v36, v2, v43
	v_mul_f32_e32 v36, 0x3fb8aa3b, v36
	v_exp_f32_e32 v44, v36
	v_sub_f32_e32 v36, v2, v75
	v_mul_f32_e32 v36, 0x3fb8aa3b, v36
	v_sub_f32_e32 v3, v2, v3
	v_add_f32_e32 v76, v45, v37
	v_exp_f32_e32 v45, v36
	v_mul_f32_e32 v3, 0x3fb8aa3b, v3
	v_exp_f32_e32 v71, v3
	v_add_f32_e32 v3, v49, v37
	v_sub_f32_e32 v3, v2, v3
	v_mul_f32_e32 v3, 0x3fb8aa3b, v3
	v_sub_f32_e32 v36, v2, v76
	v_pk_mul_f32 v[44:45], v[4:5], v[44:45]
	v_exp_f32_e32 v4, v3
	v_add_f32_e32 v3, v48, v37
	v_mul_f32_e32 v36, 0x3fb8aa3b, v36
	v_sub_f32_e32 v3, v2, v3
	v_exp_f32_e32 v70, v36
	v_mul_f32_e32 v3, 0x3fb8aa3b, v3
	v_exp_f32_e32 v5, v3
	v_add_f32_e32 v3, v47, v37
	v_sub_f32_e32 v3, v2, v3
	v_mul_f32_e32 v3, 0x3fb8aa3b, v3
	v_pk_mul_f32 v[70:71], v[6:7], v[70:71]
	v_exp_f32_e32 v6, v3
	v_add_f32_e32 v3, v46, v37
	v_sub_f32_e32 v3, v2, v3
	v_mul_f32_e32 v3, 0x3fb8aa3b, v3
	v_exp_f32_e32 v7, v3
	v_add_f32_e32 v3, v53, v37
	v_pk_mul_f32 v[4:5], v[12:13], v[4:5]
	v_sub_f32_e32 v3, v2, v3
	v_pk_mul_f32 v[6:7], v[14:15], v[6:7]
	v_mul_f32_e32 v3, 0x3fb8aa3b, v3
	v_cvt_pk_bf16_f32 v7, v6, v7
	v_cvt_pk_bf16_f32 v6, v4, v5
	v_cvt_pk_bf16_f32 v5, v70, v71
	v_cvt_pk_bf16_f32 v4, v44, v45
	ds_write_b128 v42, v[4:7] offset:20480
	v_exp_f32_e32 v4, v3
	v_add_f32_e32 v3, v52, v37
	v_sub_f32_e32 v3, v2, v3
	v_mul_f32_e32 v3, 0x3fb8aa3b, v3
	v_exp_f32_e32 v5, v3
	v_add_f32_e32 v3, v51, v37
	v_sub_f32_e32 v3, v2, v3
	v_mul_f32_e32 v3, 0x3fb8aa3b, v3
	v_exp_f32_e32 v6, v3
	v_add_f32_e32 v3, v50, v37
	v_sub_f32_e32 v3, v2, v3
	v_mul_f32_e32 v3, 0x3fb8aa3b, v3
	v_exp_f32_e32 v7, v3
	v_add_f32_e32 v3, v57, v37
	v_sub_f32_e32 v3, v2, v3
	v_mul_f32_e32 v3, 0x3fb8aa3b, v3
	v_pk_mul_f32 v[14:15], v[20:21], v[4:5]
	v_exp_f32_e32 v4, v3
	v_add_f32_e32 v3, v56, v37
	v_sub_f32_e32 v3, v2, v3
	v_mul_f32_e32 v3, 0x3fb8aa3b, v3
	v_exp_f32_e32 v5, v3
	v_add_f32_e32 v3, v55, v37
	v_sub_f32_e32 v3, v2, v3
	v_mul_f32_e32 v3, 0x3fb8aa3b, v3
	v_pk_mul_f32 v[12:13], v[22:23], v[6:7]
	v_exp_f32_e32 v6, v3
	v_add_f32_e32 v3, v54, v37
	v_sub_f32_e32 v3, v2, v3
	v_mul_f32_e32 v3, 0x3fb8aa3b, v3
	v_exp_f32_e32 v7, v3
	v_add_f32_e32 v3, v61, v37
	v_pk_mul_f32 v[4:5], v[28:29], v[4:5]
	v_sub_f32_e32 v3, v2, v3
	v_pk_mul_f32 v[6:7], v[30:31], v[6:7]
	v_mul_f32_e32 v3, 0x3fb8aa3b, v3
	v_cvt_pk_bf16_f32 v7, v6, v7
	v_cvt_pk_bf16_f32 v6, v4, v5
	v_cvt_pk_bf16_f32 v5, v12, v13
	v_cvt_pk_bf16_f32 v4, v14, v15
	ds_write_b128 v42, v[4:7] offset:20496
	v_exp_f32_e32 v4, v3
	v_add_f32_e32 v3, v60, v37
	v_sub_f32_e32 v3, v2, v3
	v_mul_f32_e32 v3, 0x3fb8aa3b, v3
	v_exp_f32_e32 v5, v3
	v_add_f32_e32 v3, v59, v37
	v_sub_f32_e32 v3, v2, v3
	v_mul_f32_e32 v3, 0x3fb8aa3b, v3
	v_exp_f32_e32 v6, v3
	v_add_f32_e32 v3, v58, v37
	v_sub_f32_e32 v3, v2, v3
	v_mul_f32_e32 v3, 0x3fb8aa3b, v3
	v_exp_f32_e32 v7, v3
	v_add_f32_e32 v3, v65, v37
	v_sub_f32_e32 v3, v2, v3
	v_mul_f32_e32 v3, 0x3fb8aa3b, v3
	v_pk_mul_f32 v[14:15], v[32:33], v[4:5]
	v_exp_f32_e32 v4, v3
	v_add_f32_e32 v3, v64, v37
	v_sub_f32_e32 v3, v2, v3
	v_mul_f32_e32 v3, 0x3fb8aa3b, v3
	v_exp_f32_e32 v5, v3
	v_add_f32_e32 v3, v63, v37
	v_sub_f32_e32 v3, v2, v3
	v_mul_f32_e32 v3, 0x3fb8aa3b, v3
	v_pk_mul_f32 v[12:13], v[34:35], v[6:7]
	v_exp_f32_e32 v6, v3
	v_add_f32_e32 v3, v62, v37
	v_sub_f32_e32 v3, v2, v3
	v_mul_f32_e32 v3, 0x3fb8aa3b, v3
	v_exp_f32_e32 v7, v3
	v_add_f32_e32 v3, v69, v37
	v_pk_mul_f32 v[4:5], v[24:25], v[4:5]
	v_sub_f32_e32 v3, v2, v3
	v_pk_mul_f32 v[6:7], v[26:27], v[6:7]
	v_mul_f32_e32 v3, 0x3fb8aa3b, v3
	v_cvt_pk_bf16_f32 v7, v6, v7
	v_cvt_pk_bf16_f32 v6, v4, v5
	v_cvt_pk_bf16_f32 v5, v12, v13
	v_cvt_pk_bf16_f32 v4, v14, v15
	ds_write_b128 v42, v[4:7] offset:20512
	v_exp_f32_e32 v4, v3
	v_add_f32_e32 v3, v68, v37
	v_sub_f32_e32 v3, v2, v3
	v_mul_f32_e32 v3, 0x3fb8aa3b, v3
	v_exp_f32_e32 v5, v3
	v_add_f32_e32 v3, v37, v67
	v_sub_f32_e32 v3, v2, v3
	v_add_f32_e32 v0, v37, v0
	v_mul_f32_e32 v3, 0x3fb8aa3b, v3
	v_sub_f32_e32 v0, v2, v0
	v_exp_f32_e32 v6, v3
	v_add_f32_e32 v3, v37, v66
	v_mul_f32_e32 v0, 0x3fb8aa3b, v0
	v_sub_f32_e32 v3, v2, v3
	v_pk_mul_f32 v[14:15], v[16:17], v[4:5]
	v_exp_f32_e32 v4, v0
	v_add_f32_e32 v0, v37, v72
	v_mul_f32_e32 v3, 0x3fb8aa3b, v3
	v_sub_f32_e32 v0, v2, v0
	v_exp_f32_e32 v7, v3
	v_mul_f32_e32 v0, 0x3fb8aa3b, v0
	v_exp_f32_e32 v5, v0
	v_add_f32_e32 v0, v37, v73
	v_sub_f32_e32 v0, v2, v0
	v_mul_f32_e32 v0, 0x3fb8aa3b, v0
	v_pk_mul_f32 v[12:13], v[18:19], v[6:7]
	v_exp_f32_e32 v6, v0
	v_add_f32_e32 v0, v37, v74
	v_sub_f32_e32 v0, v2, v0
	v_mul_f32_e32 v0, 0x3fb8aa3b, v0
	v_exp_f32_e32 v7, v0
	v_pk_mul_f32 v[4:5], v[8:9], v[4:5]
	v_pk_mul_f32 v[6:7], v[10:11], v[6:7]
	s_nop 0
	v_cvt_pk_bf16_f32 v7, v6, v7
	v_cvt_pk_bf16_f32 v6, v4, v5
	v_cvt_pk_bf16_f32 v5, v12, v13
	v_cvt_pk_bf16_f32 v4, v14, v15
	ds_write_b128 v42, v[4:7] offset:20528
	s_and_saveexec_b64 s[0:1], vcc
	s_xor_b64 s[0:1], exec, s[0:1]
	s_ashr_i32 s17, s16, 31
	s_or_saveexec_b64 s[0:1], s[0:1]
	v_mov_b64_e32 v[4:5], s[16:17]
	s_xor_b64 exec, exec, s[0:1]
	s_cbranch_execz .LBB0_144
	v_mul_f32_e32 v0, 0x3fb8aa3b, v2
	v_exp_f32_e32 v0, v0
	s_ashr_i32 s17, s16, 31
	s_lshl_b64 s[4:5], s[16:17], 9
	s_add_u32 s4, s18, s4
	s_addc_u32 s5, s19, s5
	v_mov_b64_e32 v[4:5], s[16:17]
	global_store_dword v41, v0, s[4:5]
	s_branch .LBB0_144
